# v23 + leading half's key-group-0 exp/sum/pack moved from before its barrier into the first P.V gap (lg0y)
# baseline (speedup 1.0000x reference)
.LqL_g0:
	s_waitcnt vmcnt(8) lgkmcnt(0)
	s_barrier
	s_add_i32 s54, s33, 1
	s_setprio 1
	v_exp_f32_e32 v64, v64
	v_exp_f32_e32 v65, v65
	v_exp_f32_e32 v66, v66
	v_exp_f32_e32 v67, v67
	v_add_f32_e32 v184, v64, v65
	v_exp_f32_e32 v68, v68
	v_exp_f32_e32 v69, v69
	v_cvt_pk_bf16_f32 v64, v64, v65
	v_add_f32_e32 v185, v66, v67
	v_cvt_pk_bf16_f32 v65, v66, v67
	v_exp_f32_e32 v70, v70
	v_exp_f32_e32 v71, v71
	v_add_f32_e32 v186, v68, v69
	v_cvt_pk_bf16_f32 v66, v68, v69
	v_add_f32_e32 v184, v184, v185
	v_add_f32_e32 v187, v70, v71
	v_cvt_pk_bf16_f32 v67, v70, v71
	v_add_f32_e32 v186, v186, v187
	v_add_f32_e32 v184, v184, v186
	v_add_f32_e32 v206, v206, v184
	s_cmp_eq_u32 s54, 1
	s_cbranch_scc1 .LqL_full
	s_cmp_eq_u32 s54, 29
	s_cbranch_scc1 .LqL_full
	s_add_u32 s70, s70, 0x2000
	s_addc_u32 s71, s71, 0
	s_add_u32 s66, s66, 0x80
	s_addc_u32 s67, s67, 0
